# k25 + L2 warm-up loads at the start of every context-row sub-unit GEMM (1/8 slice of the shared B tile per workgroup + own A rows), so the 3-deep latency-bound ring hits L2
# baseline (speedup 1.0000x reference)
; template <class Epi>
; __device__ __forceinline__ void gemm_sub(LAS unsigned char* lds, const int tid, const Gemm g, const Unit u, const int sub, const Epi& E) {
;     ...
;     const int ro = (sub >> 2) * 128 + (sub & 3) * 16, K = g.K, nt = K / BK, lda = g.lda;
;     constexpr int SBUF = 2 * HTB + 4096;
;     unsigned voffB[2], voffA;
; #pragma unroll
;     for (int i = 0; i < 2; ++i) { int R, C; stage_rc(tid * 16 + i * 8192, R, C); const int Rb = (R & ~31) + perm32(R & 31); voffB[i] = (unsigned)(Rb * K + C) * 2u; }
;     { int R, C; stage_rc((tid & 255) * 16, R, C); voffA = (unsigned)(((R & 15) + 64 * (R >> 4)) * lda + C) * 2u; }
;     const char* cA = (const char*)g.A + (size_t)(u.pm * BM + ro) * lda * 2;
;     const char* cB = (const char*)g.Bt + (size_t)u.pn * BM * K * 2;
;     const size_t hstepB = (size_t)HALF * K * 2;
;     const unsigned ldsw = (unsigned)wid * 1024u, ldswA = (unsigned)(wid & 3) * 1024u;
;     const int aoff = lds_byte(wr * 16 + fr, fq * 8), boff = lds_byte(wc * 32 + fr, fq * 8);
;     ...
;     f32x4 acc[1][2][1][2];
; #pragma unroll
;     for (int bj = 0; bj < 2; ++bj)
; #pragma unroll
;         for (int n = 0; n < 2; ++n) acc[0][bj][0][n] = (f32x4){0.f, 0.f, 0.f, 0.f};
;     __builtin_amdgcn_s_barrier();
;     PGS_STAGE(0, 0); PGS_STAGE(1, 1);
.LBB0_492:
	s_cmp_lt_i32 s31, 64
	s_cselect_b64 s[0:1], -1, 0
	s_and_b64 s[0:1], s[74:75], s[0:1]
	s_and_b64 vcc, exec, s[0:1]
	s_cbranch_vccnz .LBB0_491
	s_lshl_b32 s0, s27, 16
	s_lshl_b32 s1, s30, 11
	s_and_b32 s0, s0, 0x40000
	s_and_b32 s1, s1, 0x80000
	s_or_b32 s0, s1, s0
	s_and_b32 s1, s26, 3
	s_lshl_b32 s1, s1, 15
	s_or_b32 s0, s0, s1
	s_lshl_b32 s1, s31, 4
	s_lshl_b32 s2, s31, 5
	s_and_b32 s1, s1, 48
	s_and_b32 s3, s2, 0x80
	s_and_b32 s7, s2, 0x100
	s_or_b32 s6, s3, s1
	s_bitset1_b32 s7, 14
	s_or_b32 s28, s0, 0x2000000
	s_ashr_i32 s0, s31, 4
	v_readfirstlane_b32 s62, v184
	s_or_b32 s1, s6, s7
	v_lshl_add_u64 v[18:19], v[28:29], 0, s[28:29]
	s_ashr_i32 s10, s62, 6
	s_lshl_b32 s28, s1, 11
	s_ashr_i32 s1, s0, 31
	s_and_b32 s17, s10, 3
	s_lshl_b64 s[2:3], s[0:1], 19
	v_readlane_b32 s4, v249, 24
	v_readlane_b32 s5, v249, 25
	s_add_u32 s4, s4, s2
	s_addc_u32 s5, s5, s3
	s_and_b32 s100, s31, 7
	s_lshl_b32 s100, s100, 16
	v_lshlrev_b32_e32 v49, 7, v184
	v_add_u32_e32 v49, s100, v49
	global_load_dword v49, v49, s[4:5]
	s_lshl_b32 s63, s10, 10
	s_add_i32 s66, s63, 0
	s_ashr_i32 s16, s62, 8
	v_lshl_add_u64 v[2:3], s[4:5], 0, v[0:1]
	s_mov_b32 m0, s66
	s_lshl_b32 s1, s17, 10
	s_lshl_b32 s64, s16, 11
	s_lshl_b32 s65, s17, 12
	s_barrier
	global_load_lds_dwordx4 v[2:3], off
	s_add_i32 m0, s66, 0x2000
	s_add_u32 s10, s4, 0x40000
	v_lshl_add_u64 v[4:5], s[4:5], 0, v[146:147]
	s_addc_u32 s11, s5, 0
	global_load_lds_dwordx4 v[4:5], off
	s_add_i32 m0, s66, 0x4000
	v_lshl_add_u64 v[6:7], s[10:11], 0, v[0:1]
	global_load_lds_dwordx4 v[6:7], off
	v_lshl_add_u64 v[6:7], s[10:11], 0, v[146:147]
	s_add_i32 m0, s66, 0x6000
	s_add_i32 s10, s1, 0
	s_mov_b64 s[36:37], 0x80
	global_load_lds_dwordx4 v[6:7], off
	v_lshl_add_u64 v[6:7], v[26:27], 0, s[28:29]
	s_add_i32 m0, s10, 0x8000
	v_lshl_add_u64 v[2:3], v[2:3], 0, s[36:37]
	global_load_lds_dwordx4 v[6:7], off
	v_and_b32_e32 v46, 3, v184
	v_bfe_u32 v47, v184, 6, 1
	v_lshl_or_b32 v46, v47, 2, v46
	v_bfe_u32 v47, v184, 8, 1
	v_lshl_or_b32 v46, v47, 3, v46
	v_lshlrev_b32_e32 v46, 7, v46
	v_mov_b32_e32 v47, 0
	v_lshl_add_u64 v[46:47], v[46:47], 0, v[6:7]
	global_load_dword v48, v[46:47], off
	s_add_i32 m0, s66, 0x9000
	v_mov_b32_e32 v10, 0
	global_load_lds_dwordx4 v[2:3], off
	s_add_i32 m0, s66, 0xb000
	s_add_u32 s4, s4, 0x40080
	v_lshl_add_u64 v[2:3], v[4:5], 0, s[36:37]
	s_addc_u32 s5, s5, 0
	global_load_lds_dwordx4 v[2:3], off
	s_add_i32 m0, s66, 0xd000
	v_lshl_add_u64 v[2:3], s[4:5], 0, v[0:1]
	global_load_lds_dwordx4 v[2:3], off
	v_lshl_add_u64 v[2:3], s[4:5], 0, v[146:147]
	s_add_i32 m0, s66, 0xf000
	v_lshl_add_u64 v[20:21], v[30:31], 0, s[2:3]
	global_load_lds_dwordx4 v[2:3], off
	v_lshl_add_u64 v[2:3], v[6:7], 0, s[36:37]
	s_add_i32 m0, s10, 0x11000
	v_lshl_add_u64 v[22:23], v[32:33], 0, s[2:3]
	global_load_lds_dwordx4 v[2:3], off
	s_mov_b32 s28, 0
	s_mov_b64 s[2:3], 0
	s_mov_b32 s66, 0
	v_mov_b32_e32 v11, v10
	v_mov_b32_e32 v12, v10
	v_mov_b32_e32 v13, v10
	v_mov_b32_e32 v14, v10
	v_mov_b32_e32 v15, v10
	v_mov_b32_e32 v16, v10
	v_mov_b32_e32 v17, v10
	v_mov_b32_e32 v6, v10
	v_mov_b32_e32 v7, v10
	v_mov_b32_e32 v8, v10
	v_mov_b32_e32 v9, v10
	v_mov_b32_e32 v2, v10
	v_mov_b32_e32 v3, v10
	v_mov_b32_e32 v4, v10
	v_mov_b32_e32 v5, v10
	s_branch .LBB0_495

; template <class Epi>
; __device__ __forceinline__ void gemm_sub(LAS unsigned char* lds, const int tid, const Gemm g, const Unit u, const int sub, const Epi& E) {
;     ...
;     const int ro = (sub >> 2) * 128 + (sub & 3) * 16, K = g.K, nt = K / BK, lda = g.lda;
;     constexpr int SBUF = 2 * HTB + 4096;
;     unsigned voffB[2], voffA;
; #pragma unroll
;     for (int i = 0; i < 2; ++i) { int R, C; stage_rc(tid * 16 + i * 8192, R, C); const int Rb = (R & ~31) + perm32(R & 31); voffB[i] = (unsigned)(Rb * K + C) * 2u; }
;     { int R, C; stage_rc((tid & 255) * 16, R, C); voffA = (unsigned)(((R & 15) + 64 * (R >> 4)) * lda + C) * 2u; }
;     const char* cA = (const char*)g.A + (size_t)(u.pm * BM + ro) * lda * 2;
;     const char* cB = (const char*)g.Bt + (size_t)u.pn * BM * K * 2;
;     const size_t hstepB = (size_t)HALF * K * 2;
;     const unsigned ldsw = (unsigned)wid * 1024u, ldswA = (unsigned)(wid & 3) * 1024u;
;     const int aoff = lds_byte(wr * 16 + fr, fq * 8), boff = lds_byte(wc * 32 + fr, fq * 8);
;     ...
;     f32x4 acc[1][2][1][2];
; #pragma unroll
;     for (int bj = 0; bj < 2; ++bj)
; #pragma unroll
;         for (int n = 0; n < 2; ++n) acc[0][bj][0][n] = (f32x4){0.f, 0.f, 0.f, 0.f};
;     __builtin_amdgcn_s_barrier();
;     PGS_STAGE(0, 0); PGS_STAGE(1, 1);
.LBB0_1294:
	s_lshl_b32 s1, s11, 3
	s_and_b32 s1, s1, 56
	s_ashr_i32 s2, s11, 3
	s_add_i32 s1, s1, s2
	s_lshl_b32 s3, s2, 4
	s_lshl_b32 s67, s2, 5
	s_ashr_i32 s4, s1, 4
	s_and_b32 s66, s3, 48
	s_and_b32 s68, s67, 0x80
	s_lshl_b32 s1, s1, 5
	s_and_b32 s1, s1, 0x100
	s_or_b32 s2, s66, s68
	v_readfirstlane_b32 s6, v146
	s_or_b32 s17, s2, s1
	s_lshl_b32 s0, s10, 5
	s_ashr_i32 s7, s6, 6
	s_bitset1_b32 s17, 14
	s_ashr_i32 s5, s4, 31
	s_and_b32 s0, s0, 0x100
	s_and_b32 s16, s7, 3
	s_lshl_b32 s28, s17, 12
	s_lshl_b64 s[2:3], s[4:5], 19
	s_lshl_b32 s26, s7, 10
	s_ashr_i32 s5, s6, 8
	v_readlane_b32 s6, v254, 15
	v_readlane_b32 s7, v254, 16
	s_add_u32 s6, s6, s2
	s_addc_u32 s7, s7, s3
	s_lshr_b32 s100, s11, 3
	s_and_b32 s100, s100, 7
	s_lshl_b32 s100, s100, 16
	v_lshlrev_b32_e32 v49, 7, v146
	v_add_u32_e32 v49, s100, v49
	global_load_dword v49, v49, s[6:7]
	s_add_i32 s1, s26, 0
	v_lshl_add_u64 v[2:3], s[6:7], 0, v[0:1]
	s_mov_b32 m0, s1
	s_lshl_b32 s27, s5, 11
	s_lshl_b32 s30, s16, 12
	s_barrier
	global_load_lds_dwordx4 v[2:3], off
	s_add_i32 m0, s1, 0x2000
	s_add_u32 s8, s6, 0x40000
	v_lshl_add_u64 v[4:5], s[6:7], 0, v[130:131]
	s_addc_u32 s9, s7, 0
	global_load_lds_dwordx4 v[4:5], off
	s_add_i32 m0, s1, 0x4000
	v_lshl_add_u64 v[6:7], s[8:9], 0, v[0:1]
	s_lshl_b32 s31, s16, 10
	global_load_lds_dwordx4 v[6:7], off
	v_lshl_add_u64 v[6:7], s[8:9], 0, v[130:131]
	s_add_i32 m0, s1, 0x6000
	s_add_i32 s8, s31, 0
	global_load_lds_dwordx4 v[6:7], off
	v_lshl_add_u64 v[6:7], v[18:19], 0, s[28:29]
	s_add_i32 m0, s8, 0x8000
	s_mov_b64 s[36:37], 0x80
	global_load_lds_dwordx4 v[6:7], off
	v_and_b32_e32 v46, 3, v146
	v_bfe_u32 v47, v146, 6, 1
	v_lshl_or_b32 v46, v47, 2, v46
	v_bfe_u32 v47, v146, 8, 1
	v_lshl_or_b32 v46, v47, 3, v46
	v_lshlrev_b32_e32 v46, 7, v46
	v_mov_b32_e32 v47, 0
	v_lshl_add_u64 v[46:47], v[46:47], 0, v[6:7]
	global_load_dword v48, v[46:47], off
	s_add_i32 m0, s1, 0x9000
	v_lshl_add_u64 v[2:3], v[2:3], 0, s[36:37]
	global_load_lds_dwordx4 v[2:3], off
	s_add_i32 m0, s1, 0xb000
	s_add_u32 s6, s6, 0x40080
	v_lshl_add_u64 v[2:3], v[4:5], 0, s[36:37]
	s_addc_u32 s7, s7, 0
	global_load_lds_dwordx4 v[2:3], off
	s_add_i32 m0, s1, 0xd000
	v_lshl_add_u64 v[2:3], s[6:7], 0, v[0:1]
	global_load_lds_dwordx4 v[2:3], off
	v_lshl_add_u64 v[2:3], s[6:7], 0, v[130:131]
	s_add_i32 m0, s1, 0xf000
	s_add_i32 s0, s0, s67
	global_load_lds_dwordx4 v[2:3], off
	v_lshl_add_u64 v[2:3], v[6:7], 0, s[36:37]
	s_add_i32 m0, s8, 0x11000
	s_and_b32 s0, s0, 0x100
	global_load_lds_dwordx4 v[2:3], off
	s_or_b32 s0, s0, s68
	s_or_b32 s0, s0, s66
	s_lshl_b32 s0, s0, 12
	s_or_b32 s28, s0, 0x4000000
	v_mov_b32_e32 v10, 0
	v_lshl_add_u64 v[26:27], v[20:21], 0, s[28:29]
	v_lshl_add_u64 v[28:29], v[22:23], 0, s[2:3]
	v_lshl_add_u64 v[30:31], v[24:25], 0, s[2:3]
	s_mov_b32 s28, 0
	s_mov_b64 s[6:7], 0
	s_mov_b32 s66, 0
	v_mov_b32_e32 v11, v10
	v_mov_b32_e32 v12, v10
	v_mov_b32_e32 v13, v10
	v_mov_b32_e32 v14, v10
	v_mov_b32_e32 v15, v10
	v_mov_b32_e32 v16, v10
	v_mov_b32_e32 v17, v10
	v_mov_b32_e32 v6, v10
	v_mov_b32_e32 v7, v10
	v_mov_b32_e32 v8, v10
	v_mov_b32_e32 v9, v10
	v_mov_b32_e32 v2, v10
	v_mov_b32_e32 v3, v10
	v_mov_b32_e32 v4, v10
	v_mov_b32_e32 v5, v10
	s_branch .LBB0_1296

; template <class Epi>
; __device__ __forceinline__ void gemm_sub(LAS unsigned char* lds, const int tid, const Gemm g, const Unit u, const int sub, const Epi& E) {
;     ...
;     const int ro = (sub >> 2) * 128 + (sub & 3) * 16, K = g.K, nt = K / BK, lda = g.lda;
;     constexpr int SBUF = 2 * HTB + 4096;
;     unsigned voffB[2], voffA;
; #pragma unroll
;     for (int i = 0; i < 2; ++i) { int R, C; stage_rc(tid * 16 + i * 8192, R, C); const int Rb = (R & ~31) + perm32(R & 31); voffB[i] = (unsigned)(Rb * K + C) * 2u; }
;     { int R, C; stage_rc((tid & 255) * 16, R, C); voffA = (unsigned)(((R & 15) + 64 * (R >> 4)) * lda + C) * 2u; }
;     const char* cA = (const char*)g.A + (size_t)(u.pm * BM + ro) * lda * 2;
;     const char* cB = (const char*)g.Bt + (size_t)u.pn * BM * K * 2;
;     const size_t hstepB = (size_t)HALF * K * 2;
;     const unsigned ldsw = (unsigned)wid * 1024u, ldswA = (unsigned)(wid & 3) * 1024u;
;     const int aoff = lds_byte(wr * 16 + fr, fq * 8), boff = lds_byte(wc * 32 + fr, fq * 8);
;     ...
;     f32x4 acc[1][2][1][2];
; #pragma unroll
;     for (int bj = 0; bj < 2; ++bj)
; #pragma unroll
;         for (int n = 0; n < 2; ++n) acc[0][bj][0][n] = (f32x4){0.f, 0.f, 0.f, 0.f};
;     __builtin_amdgcn_s_barrier();
;     PGS_STAGE(0, 0); PGS_STAGE(1, 1);
.LBB0_1343:
	s_lshl_b32 s1, s11, 3
	s_and_b32 s1, s1, 56
	s_ashr_i32 s2, s11, 3
	s_add_i32 s1, s1, s2
	s_lshl_b32 s3, s2, 4
	s_lshl_b32 s63, s2, 5
	s_ashr_i32 s4, s1, 4
	s_and_b32 s62, s3, 48
	s_and_b32 s64, s63, 0x80
	s_lshl_b32 s1, s1, 5
	s_and_b32 s1, s1, 0x100
	s_or_b32 s2, s62, s64
	v_readfirstlane_b32 s6, v147
	s_or_b32 s17, s2, s1
	s_lshl_b32 s0, s10, 5
	s_ashr_i32 s7, s6, 6
	s_bitset1_b32 s17, 14
	s_ashr_i32 s5, s4, 31
	s_and_b32 s0, s0, 0x100
	s_and_b32 s16, s7, 3
	s_lshl_b32 s28, s17, 12
	s_lshl_b64 s[2:3], s[4:5], 19
	s_lshl_b32 s26, s7, 10
	s_ashr_i32 s5, s6, 8
	v_readlane_b32 s6, v254, 29
	v_readlane_b32 s7, v254, 30
	s_add_u32 s6, s6, s2
	s_addc_u32 s7, s7, s3
	s_lshr_b32 s100, s11, 3
	s_and_b32 s100, s100, 7
	s_lshl_b32 s100, s100, 16
	v_lshlrev_b32_e32 v49, 7, v147
	v_add_u32_e32 v49, s100, v49
	global_load_dword v49, v49, s[6:7]
	s_add_i32 s1, s26, 0
	v_lshl_add_u64 v[2:3], s[6:7], 0, v[0:1]
	s_mov_b32 m0, s1
	s_lshl_b32 s27, s5, 11
	s_lshl_b32 s30, s16, 12
	s_barrier
	global_load_lds_dwordx4 v[2:3], off
	s_add_i32 m0, s1, 0x2000
	s_add_u32 s8, s6, 0x40000
	v_lshl_add_u64 v[4:5], s[6:7], 0, v[148:149]
	s_addc_u32 s9, s7, 0
	global_load_lds_dwordx4 v[4:5], off
	s_add_i32 m0, s1, 0x4000
	v_lshl_add_u64 v[6:7], s[8:9], 0, v[0:1]
	s_lshl_b32 s31, s16, 10
	global_load_lds_dwordx4 v[6:7], off
	v_lshl_add_u64 v[6:7], s[8:9], 0, v[148:149]
	s_add_i32 m0, s1, 0x6000
	s_add_i32 s8, s31, 0
	global_load_lds_dwordx4 v[6:7], off
	v_lshl_add_u64 v[6:7], v[18:19], 0, s[28:29]
	s_add_i32 m0, s8, 0x8000
	s_mov_b64 s[36:37], 0x80
	global_load_lds_dwordx4 v[6:7], off
	v_and_b32_e32 v46, 3, v147
	v_bfe_u32 v47, v147, 6, 1
	v_lshl_or_b32 v46, v47, 2, v46
	v_bfe_u32 v47, v147, 8, 1
	v_lshl_or_b32 v46, v47, 3, v46
	v_lshlrev_b32_e32 v46, 7, v46
	v_mov_b32_e32 v47, 0
	v_lshl_add_u64 v[46:47], v[46:47], 0, v[6:7]
	global_load_dword v48, v[46:47], off
	s_add_i32 m0, s1, 0x9000
	v_lshl_add_u64 v[2:3], v[2:3], 0, s[36:37]
	global_load_lds_dwordx4 v[2:3], off
	s_add_i32 m0, s1, 0xb000
	s_add_u32 s6, s6, 0x40080
	v_lshl_add_u64 v[2:3], v[4:5], 0, s[36:37]
	s_addc_u32 s7, s7, 0
	global_load_lds_dwordx4 v[2:3], off
	s_add_i32 m0, s1, 0xd000
	v_lshl_add_u64 v[2:3], s[6:7], 0, v[0:1]
	global_load_lds_dwordx4 v[2:3], off
	v_lshl_add_u64 v[2:3], s[6:7], 0, v[148:149]
	s_add_i32 m0, s1, 0xf000
	s_add_i32 s0, s0, s63
	global_load_lds_dwordx4 v[2:3], off
	v_lshl_add_u64 v[2:3], v[6:7], 0, s[36:37]
	s_add_i32 m0, s8, 0x11000
	s_and_b32 s0, s0, 0x100
	global_load_lds_dwordx4 v[2:3], off
	s_or_b32 s0, s0, s64
	s_or_b32 s0, s0, s62
	s_lshl_b32 s0, s0, 12
	s_or_b32 s28, s0, 0x4000000
	v_mov_b32_e32 v6, 0
	v_lshl_add_u64 v[26:27], v[20:21], 0, s[28:29]
	v_lshl_add_u64 v[28:29], v[22:23], 0, s[2:3]
	v_lshl_add_u64 v[30:31], v[24:25], 0, s[2:3]
	s_mov_b32 s28, 0
	s_mov_b64 s[6:7], 0
	s_mov_b32 s62, 0
	v_mov_b32_e32 v7, v6
	v_mov_b32_e32 v8, v6
	v_mov_b32_e32 v9, v6
	v_mov_b32_e32 v14, v6
	v_mov_b32_e32 v15, v6
	v_mov_b32_e32 v16, v6
	v_mov_b32_e32 v17, v6
	v_mov_b32_e32 v10, v6
	v_mov_b32_e32 v11, v6
	v_mov_b32_e32 v12, v6
	v_mov_b32_e32 v13, v6
	v_mov_b32_e32 v2, v6
	v_mov_b32_e32 v3, v6
	v_mov_b32_e32 v4, v6
	v_mov_b32_e32 v5, v6
	s_branch .LBB0_1345

; template <class Epi>
; __device__ __forceinline__ void gemm_sub(LAS unsigned char* lds, const int tid, const Gemm g, const Unit u, const int sub, const Epi& E) {
;     ...
;     const int ro = (sub >> 2) * 128 + (sub & 3) * 16, K = g.K, nt = K / BK, lda = g.lda;
;     constexpr int SBUF = 2 * HTB + 4096;
;     unsigned voffB[2], voffA;
; #pragma unroll
;     for (int i = 0; i < 2; ++i) { int R, C; stage_rc(tid * 16 + i * 8192, R, C); const int Rb = (R & ~31) + perm32(R & 31); voffB[i] = (unsigned)(Rb * K + C) * 2u; }
;     { int R, C; stage_rc((tid & 255) * 16, R, C); voffA = (unsigned)(((R & 15) + 64 * (R >> 4)) * lda + C) * 2u; }
;     const char* cA = (const char*)g.A + (size_t)(u.pm * BM + ro) * lda * 2;
;     const char* cB = (const char*)g.Bt + (size_t)u.pn * BM * K * 2;
;     const size_t hstepB = (size_t)HALF * K * 2;
;     const unsigned ldsw = (unsigned)wid * 1024u, ldswA = (unsigned)(wid & 3) * 1024u;
;     const int aoff = lds_byte(wr * 16 + fr, fq * 8), boff = lds_byte(wc * 32 + fr, fq * 8);
;     ...
;     f32x4 acc[1][2][1][2];
; #pragma unroll
;     for (int bj = 0; bj < 2; ++bj)
; #pragma unroll
;         for (int n = 0; n < 2; ++n) acc[0][bj][0][n] = (f32x4){0.f, 0.f, 0.f, 0.f};
;     __builtin_amdgcn_s_barrier();
;     PGS_STAGE(0, 0); PGS_STAGE(1, 1);
.LBB0_1706:
	s_lshl_b32 s4, s10, 5
	s_and_b32 s67, s4, 0x100
	s_lshl_b32 s4, s11, 3
	s_and_b32 s4, s4, 56
	s_ashr_i32 s5, s11, 3
	s_add_i32 s4, s4, s5
	s_lshl_b32 s70, s5, 5
	s_lshl_b32 s5, s5, 4
	s_ashr_i32 s62, s4, 4
	s_and_b32 s71, s70, 0x80
	s_and_b32 s72, s5, 48
	s_lshl_b32 s4, s4, 5
	s_and_b32 s4, s4, 0x100
	s_or_b32 s5, s72, s71
	v_readfirstlane_b32 s16, v191
	s_or_b32 s17, s5, s4
	s_ashr_i32 s27, s16, 6
	s_bitset1_b32 s17, 14
	s_ashr_i32 s63, s62, 31
	s_and_b32 s26, s27, 3
	s_ashr_i32 s16, s16, 8
	s_lshl_b32 s28, s17, 11
	s_lshl_b64 s[4:5], s[62:63], 19
	v_readlane_b32 s30, v252, 26
	v_readlane_b32 s31, v252, 27
	s_add_u32 s30, s30, s4
	s_addc_u32 s31, s31, s5
	s_lshr_b32 s100, s11, 3
	s_and_b32 s100, s100, 7
	s_lshl_b32 s100, s100, 16
	v_lshlrev_b32_e32 v49, 7, v191
	v_add_u32_e32 v49, s100, v49
	global_load_dword v49, v49, s[30:31]
	s_lshl_b32 s63, s27, 10
	s_add_i32 s73, s63, 0
	s_waitcnt lgkmcnt(0)
	v_lshl_add_u64 v[2:3], s[30:31], 0, v[34:35]
	s_mov_b32 m0, s73
	s_lshl_b32 s27, s16, 4
	s_lshl_b32 s64, s26, 10
	s_lshl_b32 s65, s16, 11
	s_lshl_b32 s66, s26, 12
	s_barrier
	global_load_lds_dwordx4 v[2:3], off
	s_add_i32 m0, s73, 0x2000
	s_add_u32 s68, s30, 0x40000
	v_lshl_add_u64 v[4:5], s[30:31], 0, v[170:171]
	s_addc_u32 s69, s31, 0
	global_load_lds_dwordx4 v[4:5], off
	s_add_i32 m0, s73, 0x4000
	v_lshl_add_u64 v[6:7], s[68:69], 0, v[34:35]
	global_load_lds_dwordx4 v[6:7], off
	v_lshl_add_u64 v[6:7], s[68:69], 0, v[170:171]
	s_add_i32 m0, s73, 0x6000
	s_mov_b64 s[36:37], 0x80
	global_load_lds_dwordx4 v[6:7], off
	v_lshl_add_u64 v[6:7], v[36:37], 0, s[28:29]
	s_add_i32 s28, s64, 0
	s_add_i32 m0, s28, 0x8000
	v_lshl_add_u64 v[2:3], v[2:3], 0, s[36:37]
	global_load_lds_dwordx4 v[6:7], off
	v_and_b32_e32 v46, 3, v191
	v_bfe_u32 v47, v191, 6, 1
	v_lshl_or_b32 v46, v47, 2, v46
	v_bfe_u32 v47, v191, 8, 1
	v_lshl_or_b32 v46, v47, 3, v46
	v_lshlrev_b32_e32 v46, 7, v46
	v_mov_b32_e32 v47, 0
	v_lshl_add_u64 v[46:47], v[46:47], 0, v[6:7]
	global_load_dword v48, v[46:47], off
	s_add_i32 m0, s73, 0x9000
	v_lshlrev_b32_e32 v0, 2, v194
	global_load_lds_dwordx4 v[2:3], off
	s_add_i32 m0, s73, 0xb000
	s_add_u32 s30, s30, 0x40080
	v_lshl_add_u64 v[2:3], v[4:5], 0, s[36:37]
	s_addc_u32 s31, s31, 0
	global_load_lds_dwordx4 v[2:3], off
	s_add_i32 m0, s73, 0xd000
	v_lshl_add_u64 v[2:3], s[30:31], 0, v[34:35]
	global_load_lds_dwordx4 v[2:3], off
	v_lshl_add_u64 v[2:3], s[30:31], 0, v[170:171]
	s_add_i32 m0, s73, 0xf000
	s_add_i32 s67, s67, s70
	global_load_lds_dwordx4 v[2:3], off
	v_lshl_add_u64 v[2:3], v[6:7], 0, s[36:37]
	s_add_i32 m0, s28, 0x11000
	s_and_b32 s28, s67, 0x100
	global_load_lds_dwordx4 v[2:3], off
	s_or_b32 s28, s28, s71
	s_or_b32 s28, s28, s72
	s_lshl_b32 s28, s28, 11
	v_and_b32_e32 v0, 32, v0
	s_bitset1_b32 s28, 25
	v_mov_b32_e32 v10, 0
	v_bitop3_b32 v0, v197, v0, v196 bitop3:0x36
	v_lshl_add_u64 v[18:19], v[38:39], 0, s[28:29]
	v_lshl_add_u64 v[20:21], v[40:41], 0, s[4:5]
	v_lshl_add_u64 v[22:23], v[42:43], 0, s[4:5]
	s_mov_b32 s28, 0
	s_mov_b64 s[4:5], 0
	s_mov_b32 s67, 0
	v_mov_b32_e32 v11, v10
	v_mov_b32_e32 v12, v10
	v_mov_b32_e32 v13, v10
	v_mov_b32_e32 v14, v10
	v_mov_b32_e32 v15, v10
	v_mov_b32_e32 v16, v10
	v_mov_b32_e32 v17, v10
	v_mov_b32_e32 v6, v10
	v_mov_b32_e32 v7, v10
	v_mov_b32_e32 v8, v10
	v_mov_b32_e32 v9, v10
	v_mov_b32_e32 v2, v10
	v_mov_b32_e32 v3, v10
	v_mov_b32_e32 v4, v10
	v_mov_b32_e32 v5, v10
	s_mov_b64 s[36:37], 0x2100100
	s_mov_b64 s[38:39], 0x2140100
	s_branch .LBB0_1708

; template <class Epi>
; __device__ __forceinline__ void gemm_sub(LAS unsigned char* lds, const int tid, const Gemm g, const Unit u, const int sub, const Epi& E) {
;     ...
;     const int ro = (sub >> 2) * 128 + (sub & 3) * 16, K = g.K, nt = K / BK, lda = g.lda;
;     constexpr int SBUF = 2 * HTB + 4096;
;     unsigned voffB[2], voffA;
; #pragma unroll
;     for (int i = 0; i < 2; ++i) { int R, C; stage_rc(tid * 16 + i * 8192, R, C); const int Rb = (R & ~31) + perm32(R & 31); voffB[i] = (unsigned)(Rb * K + C) * 2u; }
;     { int R, C; stage_rc((tid & 255) * 16, R, C); voffA = (unsigned)(((R & 15) + 64 * (R >> 4)) * lda + C) * 2u; }
;     const char* cA = (const char*)g.A + (size_t)(u.pm * BM + ro) * lda * 2;
;     const char* cB = (const char*)g.Bt + (size_t)u.pn * BM * K * 2;
;     const size_t hstepB = (size_t)HALF * K * 2;
;     const unsigned ldsw = (unsigned)wid * 1024u, ldswA = (unsigned)(wid & 3) * 1024u;
;     const int aoff = lds_byte(wr * 16 + fr, fq * 8), boff = lds_byte(wc * 32 + fr, fq * 8);
;     ...
;     f32x4 acc[1][2][1][2];
; #pragma unroll
;     for (int bj = 0; bj < 2; ++bj)
; #pragma unroll
;         for (int n = 0; n < 2; ++n) acc[0][bj][0][n] = (f32x4){0.f, 0.f, 0.f, 0.f};
;     __builtin_amdgcn_s_barrier();
;     PGS_STAGE(0, 0); PGS_STAGE(1, 1);
.LBB0_2509:
	s_lshl_b32 s6, s4, 5
	s_and_b32 s67, s6, 0x100
	s_lshl_b32 s6, s5, 3
	s_and_b32 s6, s6, 56
	s_ashr_i32 s7, s5, 3
	s_add_i32 s10, s6, s7
	s_lshl_b32 s68, s7, 5
	s_lshl_b32 s7, s7, 4
	s_ashr_i32 s6, s10, 4
	v_readfirstlane_b32 s26, v147
	s_and_b32 s69, s68, 0x80
	s_and_b32 s70, s7, 48
	s_lshl_b32 s10, s10, 5
	s_ashr_i32 s30, s26, 6
	s_ashr_i32 s7, s26, 8
	s_and_b32 s10, s10, 0x100
	s_or_b32 s26, s70, s69
	s_or_b32 s10, s26, s10
	s_and_b32 s11, s30, 3
	s_bitset1_b32 s10, 14
	s_mul_i32 s26, s6, 0x160000
	v_readlane_b32 s36, v251, 50
	s_mul_hi_i32 s27, s6, 0x160000
	v_readlane_b32 s37, v251, 51
	s_add_u32 s26, s36, s26
	s_addc_u32 s27, s37, s27
	s_lshr_b32 s100, s5, 3
	s_and_b32 s100, s100, 7
	s_mul_i32 s100, s100, 0x2c000
	v_lshlrev_b32_e32 v45, 7, v147
	v_add_u32_e32 v45, s100, v45
	v_add_u32_e32 v44, 0x10000, v45
	v_add_u32_e32 v41, 0x20000, v45
	global_load_dword v45, v45, s[26:27]
	global_load_dword v44, v44, s[26:27]
	global_load_dword v41, v41, s[26:27]
	s_lshl_b32 s63, s30, 10
	s_add_i32 s71, s63, 0
	s_waitcnt lgkmcnt(0)
	v_lshl_add_u64 v[2:3], s[26:27], 0, v[0:1]
	s_mov_b32 m0, s71
	s_lshl_b32 s62, s7, 4
	s_lshl_b32 s64, s11, 10
	s_lshl_b32 s65, s7, 11
	s_lshl_b32 s66, s11, 12
	s_barrier
	global_load_lds_dwordx4 v[2:3], off
	s_add_i32 m0, s71, 0x2000
	s_add_u32 s30, s26, 0xb0000
	v_lshl_add_u64 v[4:5], s[26:27], 0, v[142:143]
	s_addc_u32 s31, s27, 0
	global_load_lds_dwordx4 v[4:5], off
	s_add_i32 m0, s71, 0x4000
	v_lshl_add_u64 v[6:7], s[30:31], 0, v[0:1]
	s_mul_i32 s28, s10, 0x2c00
	global_load_lds_dwordx4 v[6:7], off
	v_lshl_add_u64 v[6:7], s[30:31], 0, v[142:143]
	s_add_i32 m0, s71, 0x6000
	s_mov_b64 s[30:31], 0x80
	global_load_lds_dwordx4 v[6:7], off
	v_lshl_add_u64 v[6:7], v[22:23], 0, s[28:29]
	s_add_i32 s28, s64, 0
	s_add_i32 m0, s28, 0x8000
	v_lshl_add_u64 v[2:3], v[2:3], 0, s[30:31]
	global_load_lds_dwordx4 v[6:7], off
	v_and_b32_e32 v48, 3, v147
	v_bfe_u32 v49, v147, 6, 1
	v_lshl_or_b32 v48, v49, 2, v48
	v_bfe_u32 v49, v147, 8, 1
	v_lshl_or_b32 v48, v49, 3, v48
	v_lshlrev_b32_e32 v48, 7, v48
	v_mov_b32_e32 v49, 0
	v_lshl_add_u64 v[48:49], v[48:49], 0, v[6:7]
	global_load_dword v47, v[48:49], off
	global_load_dword v47, v[48:49], off offset:2048
	s_mov_b64 s[100:101], 0x1000
	v_lshl_add_u64 v[42:43], v[48:49], 0, s[100:101]
	global_load_dword v47, v[42:43], off
	s_add_i32 m0, s71, 0x9000
	v_mov_b32_e32 v10, 0
	global_load_lds_dwordx4 v[2:3], off
	s_add_i32 m0, s71, 0xb000
	s_add_u32 s26, s26, 0xb0080
	v_lshl_add_u64 v[2:3], v[4:5], 0, s[30:31]
	s_addc_u32 s27, s27, 0
	global_load_lds_dwordx4 v[2:3], off
	s_add_i32 m0, s71, 0xd000
	v_lshl_add_u64 v[2:3], s[26:27], 0, v[0:1]
	global_load_lds_dwordx4 v[2:3], off
	v_lshl_add_u64 v[2:3], s[26:27], 0, v[142:143]
	s_add_i32 m0, s71, 0xf000
	s_add_i32 s67, s67, s68
	global_load_lds_dwordx4 v[2:3], off
	v_lshl_add_u64 v[2:3], v[6:7], 0, s[30:31]
	s_add_i32 m0, s28, 0x11000
	s_and_b32 s26, s67, 0x100
	global_load_lds_dwordx4 v[2:3], off
	s_or_b32 s26, s26, s69
	s_or_b32 s26, s26, s70
	v_lshlrev_b32_e32 v2, 2, v182
	s_bitset1_b32 s26, 14
	v_and_b32_e32 v2, 32, v2
	s_mul_i32 s28, s26, 0x2c00
	v_mad_i64_i32 v[20:21], s[26:27], s6, v208, v[26:27]
	v_mad_i64_i32 v[30:31], s[26:27], s6, v208, v[28:29]
	v_bitop3_b32 v32, v185, v2, v184 bitop3:0x36
	v_lshl_add_u64 v[18:19], v[24:25], 0, s[28:29]
	s_mov_b32 s28, 0
	s_mov_b64 s[26:27], 0
	s_mov_b32 s67, 0
	v_mov_b32_e32 v11, v10
	v_mov_b32_e32 v12, v10
	v_mov_b32_e32 v13, v10
	v_mov_b32_e32 v14, v10
	v_mov_b32_e32 v15, v10
	v_mov_b32_e32 v16, v10
	v_mov_b32_e32 v17, v10
	v_mov_b32_e32 v6, v10
	v_mov_b32_e32 v7, v10
	v_mov_b32_e32 v8, v10
	v_mov_b32_e32 v9, v10
	v_mov_b32_e32 v2, v10
	v_mov_b32_e32 v3, v10
	v_mov_b32_e32 v4, v10
	v_mov_b32_e32 v5, v10
	s_mov_b64 s[36:37], 0x2e00100
	s_mov_b64 s[38:39], 0x2eb0100
	s_branch .LBB0_2511
